# v043 with the whole instruction stream shifted by 8 bytes (two s_nop at entry): code placement test
# baseline (speedup 1.0000x reference)
_Z4mega6Params:
	s_nop 0
	s_nop 0
	s_mov_b32 s26, s2
	s_mov_b32 s25, 0
	v_cmp_eq_u32_e32 vcc, 0, v0
	s_and_saveexec_b64 s[2:3], vcc
	s_cbranch_execz .LBB0_3
	s_add_i32 s6, 0, 0x20000
	v_mov_b32_e32 v1, 0
	v_mov_b32_e32 v2, s6
	s_add_i32 s6, 0, 0x20004
	s_mov_b64 s[4:5], exec
	ds_write_b32 v2, v1
	v_mov_b32_e32 v2, s6
	ds_write_b32 v2, v1
	v_mbcnt_lo_u32_b32 v1, s4, 0
	v_mbcnt_hi_u32_b32 v1, s5, v1
	v_cmp_eq_u32_e32 vcc, 0, v1
	s_getreg_b32 s6, hwreg(HW_REG_XCC_ID, 0, 4)
	s_and_b64 s[8:9], exec, vcc
	s_mov_b64 exec, s[8:9]
	s_cbranch_execz .LBB0_3
	s_load_dwordx2 s[8:9], s[0:1], 0xf8
	s_lshl_b32 s6, s6, 8
	s_and_b32 s6, s6, 0xf00
	s_bcnt1_i32_b64 s4, s[4:5]
	v_mov_b32_e32 v1, s6
	v_mov_b32_e32 v2, s4
	s_waitcnt lgkmcnt(0)
	global_atomic_add v1, v2, s[8:9] offset:1024
